# late operand prep distributed as 512 single-chunk units over the 192 non-scan workgroups with per-chunk ready flags (was 2-chunk tiles)
# baseline (speedup 1.0000x reference)
; #define LAS __attribute__((address_space(3)))
; __device__ __forceinline__ int lane_id() { int l__; asm volatile("v_mbcnt_lo_u32_b32 %0, -1, 0\n\tv_mbcnt_hi_u32_b32 %0, -1, %0" : "=v"(l__)); return l__; }
; __global__ void __launch_bounds__(NTHR, 2) hybrid_fwd(Args args) {
;     extern __shared__ __attribute__((aligned(16))) unsigned char lds[];
;     Frame F; F.lds = (LAS unsigned char*)lds; F.wave = __builtin_amdgcn_readfirstlane(threadIdx.x >> 6);
;     F.G = gridDim.x; F.gw = blockIdx.x * NWAVES + F.wave; F.NGW = F.G * NWAVES;
;     unsigned char* ws = args.ws;
;     volatile LAS unsigned* MISC = (volatile LAS unsigned*)(F.lds + MISC_OFF);
;     unsigned* ctl = (unsigned*)(ws + WS_CTL);
;     { int l_ = lane_id(); if (F.wave == 0 && l_ < 32) MISC[l_] = 0u; }
;     __syncthreads();
;     if (blockIdx.x == 0) { v4u* z = (v4u*)(ws + WS_CTL); const v4u zero = {0u, 0u, 0u, 0u}; const int t_ = F.wave * 64 + lane_id();
; #pragma unroll
;         for (int i = 0; i < 8; ++i) z[t_ + 512 * i] = zero; }
_Z10hybrid_fwd4Args:
	s_mov_b32 s94, s2
	s_mov_b32 s98, 0
	s_mov_b32 s99, 0
	v_and_b32_e32 v1, 0x3ff, v0
	s_add_u32 s2, s0, 0xe0
	v_readfirstlane_b32 s93, v1
	s_addc_u32 s3, s1, 0
	s_cmp_lt_u32 s93, 64
	s_cselect_b64 s[4:5], -1, 0
	s_cmp_gt_u32 s93, 63
	s_load_dwordx8 s[84:91], s[0:1], 0xc0
	s_load_dword s97, s[0:1], 0xe0
	s_cselect_b64 s[6:7], -1, 0
	v_mbcnt_lo_u32_b32 v2, -1, 0
	v_mbcnt_hi_u32_b32 v2, -1, v2
	v_writelane_b32 v254, s6, 0
	v_cmp_gt_i32_e32 vcc, 32, v2
	s_nop 0
	v_writelane_b32 v254, s7, 1
	v_writelane_b32 v254, s4, 2
	s_and_b64 s[6:7], s[4:5], vcc
	s_nop 0
	v_writelane_b32 v254, s5, 3
	s_and_saveexec_b64 s[4:5], s[6:7]
	v_lshl_add_u32 v2, v2, 2, 0
	v_add_u32_e32 v2, 0x25800, v2
	v_mov_b32_e32 v3, 0
	ds_write_b32 v2, v3
	s_or_b64 exec, exec, s[4:5]
	s_cmp_lg_u32 s94, 0
	s_mov_b32 s4, 0
	s_waitcnt lgkmcnt(0)
	s_barrier
	s_cbranch_scc1 .LBB0_4
	s_and_b32 s5, s93, 0xffffffc0
	v_mbcnt_lo_u32_b32 v2, -1, 0
	v_mbcnt_hi_u32_b32 v2, -1, v2
	s_mov_b32 s6, s4
	v_add_u32_e32 v2, s5, v2
	v_ashrrev_i32_e32 v3, 31, v2
	v_lshl_add_u64 v[2:3], v[2:3], 4, s[90:91]
	s_mov_b32 s7, s4
	s_mov_b32 s5, s4
	v_mov_b64_e32 v[8:9], s[6:7]
	v_add_co_u32_e32 v4, vcc, 0x2000, v2
	v_mov_b64_e32 v[6:7], s[4:5]
	s_nop 0
	v_addc_co_u32_e32 v5, vcc, 0, v3, vcc
	global_store_dwordx4 v[4:5], v[6:9], off
	v_add_co_u32_e32 v4, vcc, 0x4000, v2
	global_store_dwordx4 v[2:3], v[6:9], off
	s_nop 0
	v_addc_co_u32_e32 v5, vcc, 0, v3, vcc
	global_store_dwordx4 v[4:5], v[6:9], off
	v_add_co_u32_e32 v4, vcc, 0x6000, v2
	s_nop 1
	v_addc_co_u32_e32 v5, vcc, 0, v3, vcc
	global_store_dwordx4 v[4:5], v[6:9], off
	v_add_co_u32_e32 v4, vcc, 0x8000, v2
	s_nop 1
	v_addc_co_u32_e32 v5, vcc, 0, v3, vcc
	global_store_dwordx4 v[4:5], v[6:9], off
	v_add_co_u32_e32 v4, vcc, 0xa000, v2
	s_nop 1
	v_addc_co_u32_e32 v5, vcc, 0, v3, vcc
	global_store_dwordx4 v[4:5], v[6:9], off
	v_add_co_u32_e32 v4, vcc, 0xc000, v2
	s_nop 1
	v_addc_co_u32_e32 v5, vcc, 0, v3, vcc
	v_add_co_u32_e32 v2, vcc, 0xe000, v2
	global_store_dwordx4 v[4:5], v[6:9], off
	s_nop 0
	v_addc_co_u32_e32 v3, vcc, 0, v3, vcc
	global_store_dwordx4 v[2:3], v[6:9], off

; #define LAS __attribute__((address_space(3)))
; __device__ __forceinline__ void p2_rwprep_tile(Frame& F, const Args& a, int t0) {
;     ...
;     __syncthreads();
;     LAS unsigned char* lw_ = F.lds + 8192 + F.wave * 10240;
;     for (int q = 0; q < 4; ++q) { const int hh = q >> 1, rb = q & 1; rw_chunk_prep(a, 2 * F.wave + hh, t0 + rb * 16, TD + rb * 16 * 64, DA + rb * 16 * 64, lw_, F.lane); }
;     __syncthreads();
; }
; __global__ void __launch_bounds__(NTHR, 2) hybrid_fwd(Args args) {
;     ...
;         for (int tile = blockIdx.x; tile < T / 32; tile += F.G) p2_rwprep_tile(F, args, tile * 32); }
.Lrw_again:
	v_cmp_eq_u32_e64 s[22:23], 15, v11
	v_lshlrev_b32_e32 v6, 2, v10
	v_and_b32_e32 v1, 60, v6
	v_cndmask_b32_e64 v167, 0, 1.0, s[22:23]
	v_cmp_eq_u32_e64 s[22:23], 1, v11
	v_lshlrev_b32_e32 v66, 2, v1
	v_lshlrev_b32_e32 v2, 7, v64
	v_cndmask_b32_e64 v168, 0, 1.0, s[22:23]
	v_cmp_eq_u32_e64 s[22:23], 2, v11
	v_lshlrev_b32_e32 v1, 1, v1
	v_ashrrev_i32_e32 v4, 4, v10
	v_cndmask_b32_e64 v169, 0, 1.0, s[22:23]
	v_cmp_eq_u32_e64 s[22:23], 3, v11
	v_add3_u32 v65, 0, v2, v1
	v_lshlrev_b32_e32 v2, 3, v4
	v_cndmask_b32_e64 v170, 0, 1.0, s[22:23]
	v_cmp_eq_u32_e64 s[22:23], 4, v11
	v_ashrrev_i32_e32 v3, 31, v2
	v_mbcnt_hi_u32_b32 v1, -1, v156
	v_cndmask_b32_e64 v171, 0, 1.0, s[22:23]
	v_cmp_eq_u32_e64 s[22:23], 5, v11
	v_lshlrev_b64 v[2:3], 1, v[2:3]
	v_and_b32_e32 v1, 64, v1
	v_cndmask_b32_e64 v172, 0, 1.0, s[22:23]
	v_cmp_eq_u32_e64 s[22:23], 6, v11
	v_lshl_add_u64 v[74:75], s[6:7], 0, v[2:3]
	v_lshl_add_u64 v[76:77], s[8:9], 0, v[2:3]
	v_add_u32_e32 v2, 48, v10
	v_cndmask_b32_e64 v173, 0, 1.0, s[22:23]
	v_cmp_eq_u32_e64 s[22:23], 7, v11
	v_and_or_b32 v2, v2, 63, v1
	v_lshlrev_b32_e32 v158, 2, v2
	v_cndmask_b32_e64 v174, 0, 1.0, s[22:23]
	v_cmp_eq_u32_e64 s[22:23], 8, v11
	v_and_or_b32 v2, v10, 63, v1
	s_mul_i32 s0, s92, 0x2800
	v_cndmask_b32_e64 v175, 0, 1.0, s[22:23]
	v_cmp_eq_u32_e64 s[22:23], 9, v11
	v_lshlrev_b32_e32 v2, 2, v2
	s_add_i32 s33, s0, 0
	v_cndmask_b32_e64 v176, 0, 1.0, s[22:23]
	v_cmp_eq_u32_e64 s[22:23], 10, v11
	v_xor_b32_e32 v159, 0x80, v2
	v_or_b32_e32 v1, v1, v11
	v_mov_b32_e32 v2, 0xc0
	v_cndmask_b32_e64 v177, 0, 1.0, s[22:23]
	v_cmp_eq_u32_e64 s[22:23], 11, v11
	v_lshlrev_b32_e32 v157, 2, v4
	v_lshl_or_b32 v160, v1, 2, v2
	v_lshl_add_u32 v1, v11, 3, s33
	v_cndmask_b32_e64 v178, 0, 1.0, s[22:23]
	v_cmp_eq_u32_e64 s[22:23], 12, v11
	v_and_b32_e32 v7, -16, v10
	v_cmp_lt_i32_e64 s[4:5], 0, v4
	v_cmp_lt_i32_e64 s[6:7], 1, v4
	v_lshl_add_u32 v161, v4, 9, v1
	v_or_b32_e32 v2, 1, v157
	v_or_b32_e32 v3, 2, v157
	v_or_b32_e32 v4, 3, v157
	v_cndmask_b32_e64 v179, 0, 1.0, s[22:23]
	v_cmp_eq_u32_e64 s[22:23], 13, v11
	v_lshlrev_b32_e32 v5, 7, v11
	v_lshl_add_u32 v162, v2, 7, v1
	v_lshl_add_u32 v163, v3, 7, v1
	v_lshl_add_u32 v164, v4, 7, v1
	v_add_u32_e32 v1, s33, v7
	v_cndmask_b32_e64 v180, 0, 1.0, s[22:23]
	v_cmp_eq_u32_e64 s[22:23], 14, v11
	v_add_u32_e32 v165, v1, v5
	v_lshl_add_u32 v166, v11, 6, v1
	v_cndmask_b32_e64 v181, 0, 1.0, s[22:23]
	v_mov_b32_e32 v1, 0x3f80
	v_cmp_eq_u32_e64 s[22:23], v157, v11
	v_add3_u32 v155, 0, v5, v7
	v_cmp_lt_i32_e32 vcc, v2, v11
	v_cndmask_b32_e64 v5, 0, v1, s[22:23]
	v_cmp_eq_u32_e64 s[22:23], v2, v11
	v_mov_b32_e32 v67, 0
	v_cmp_lt_i32_e64 s[20:21], v3, v11
	v_cndmask_b32_e64 v2, 0, 1.0, s[22:23]
	v_cmp_eq_u32_e64 s[22:23], v3, v11
	v_or_b32_e32 v78, v2, v5
	v_cmp_gt_i32_e64 s[12:13], v3, v11
	v_cndmask_b32_e64 v1, 0, v1, s[22:23]
	v_cmp_eq_u32_e64 s[22:23], v4, v11
	v_lshl_add_u64 v[68:69], s[14:15], 0, v[66:67]
	v_cmp_lt_i32_e64 s[14:15], v4, v11
	v_cndmask_b32_e64 v2, 0, 1.0, s[22:23]
	v_or_b32_e32 v79, v1, v2
	v_lshlrev_b32_e32 v2, 3, v10
	v_ashrrev_i32_e32 v3, 31, v2
	v_cmp_gt_i32_e64 s[16:17], v4, v11
	v_lshl_add_u64 v[4:5], s[90:91], 0, v[2:3]
	s_mov_b64 s[2:3], 0x19000000
	s_lshl_b32 s34, s92, 1
	v_lshl_add_u64 v[80:81], v[4:5], 0, s[2:3]
	s_mov_b64 s[2:3], 0x1b000000
	s_add_u32 s35, s90, 0x3d00000
	v_lshl_add_u64 v[82:83], v[4:5], 0, s[2:3]
	v_lshl_add_u64 v[2:3], s[88:89], 0, v[2:3]
	s_mov_b64 s[2:3], 0x4000000
	v_lshl_add_u64 v[72:73], s[36:37], 0, v[66:67]
	s_addc_u32 s36, s91, 0
	v_lshl_add_u64 v[84:85], v[2:3], 0, s[2:3]
	s_mov_b64 s[2:3], 0x6000000
	v_ashrrev_i32_e32 v1, 31, v0
	v_lshl_add_u64 v[86:87], v[2:3], 0, s[2:3]
	s_mov_b64 s[2:3], 0x1d000000
	v_lshl_add_u64 v[90:91], s[88:89], 0, v[0:1]
	s_add_u32 s37, s90, 0x1f000000
	v_and_b32_e32 v0, 3, v10
	v_lshl_add_u64 v[88:89], v[4:5], 0, s[2:3]
	s_mov_b64 s[2:3], 0x2000000
	s_addc_u32 s40, s91, 0
	v_and_or_b32 v0, v6, 48, v0
	s_or_b64 s[20:21], s[14:15], s[20:21]
	v_lshl_add_u64 v[70:71], s[82:83], 0, v[66:67]
	s_mov_b32 s1, 0
	v_lshlrev_b32_e32 v154, 2, v11
	v_cmp_eq_u32_e64 s[24:25], 0, v11
	v_cmp_lt_i32_e64 s[8:9], v157, v11
	v_cmp_gt_i32_e64 s[10:11], v157, v11
	v_cmp_gt_u32_e64 s[18:19], 16, v10
	v_add_u32_e32 v182, s33, v6
	v_lshl_add_u64 v[92:93], v[90:91], 0, s[2:3]
	v_or3_b32 v94, v10, v6, 12
	v_mov_b32_e32 v95, v67
	s_mov_b32 s41, 0xc1700000
	s_movk_i32 s44, 0x1800
	s_movk_i32 s45, 0x1000
	s_mov_b32 s52, 0xbfb8aa3b
	s_mov_b32 s53, 0x800000
	s_mov_b32 s54, 0x3f317217
	s_mov_b32 s55, 0x7f800000
	v_lshlrev_b32_e32 v183, 2, v0
	v_mov_b32_e32 v184, 0x41700000
	v_mov_b32_e32 v185, 0x41b17218
	s_or_b64 s[22:23], s[20:21], vcc
	s_mov_b32 s56, s94
	s_mov_b32 s99, 0
	s_cmp_eq_u32 s98, 1
	s_cbranch_scc0 .LBB0_323
	s_add_i32 s99, s94, -64
	s_lshr_b32 s56, s99, 1
	s_add_i32 s56, s56, 0x100
	s_branch .LBB0_323
.LBB0_322:
	s_waitcnt vmcnt(0)
	s_barrier
	s_cmp_lg_u32 s98, 1
	s_cbranch_scc1 .Lrw_step
	s_cmp_lg_u32 s92, 0
	s_cbranch_scc1 .Lrw_step
	buffer_wbl2 sc1
	s_waitcnt vmcnt(0)
	s_lshl_b32 s101, s99, 2
	s_add_i32 s101, s101, 0x8800
	v_mov_b32_e32 v204, s101
	v_mov_b32_e32 v205, 1
	s_mov_b64 exec, 1
	global_atomic_add v204, v205, s[90:91]
	s_mov_b64 exec, -1
.Lrw_step:
	s_cmp_eq_u32 s98, 1
	s_cbranch_scc0 .LBB0_347
	s_add_i32 s99, s99, 0xc0
	s_cmpk_gt_i32 s99, 0x1ff
	s_cbranch_scc1 .LBB0_347
	s_lshr_b32 s56, s99, 1
	s_add_i32 s56, s56, 0x100

; #define LAS __attribute__((address_space(3)))
; __device__ __forceinline__ v2u pk4(f32x4 v) { v2u o; o.x = pk2(v.x, v.y); o.y = pk2(v.z, v.w); return o; }
; __device__ __forceinline__ float fast_tanh(float x) { x = fminf(fmaxf(x, -15.f), 15.f); const float e = __expf(2.f * x); return (e - 1.f) / (e + 1.f); }
; __device__ __forceinline__ void p2_rwprep_tile(Frame& F, const Args& a, int t0) {
;     ...
;         const int tok = F.tid >> 4, c4 = (F.tid & 15) * 4, t = t0 + tok;
;         const f32x4 zero = {0.f, 0.f, 0.f, 0.f};
;         const f32x4 cw = ld4(ZS + (size_t)t * 256 + c4), ca = ld4(ZS + (size_t)t * 256 + 64 + c4);
;         const f32x4 pw = t > 0 ? ld4(ZS + (size_t)(t - 1) * 256 + c4) : zero, pa = t > 0 ? ld4(ZS + (size_t)(t - 1) * 256 + 64 + c4) : zero;
;         const f32x4 mw = ld4(a.in[7] + c4), ma = ld4(a.in[8] + c4);
;         f32x4 dw = cw + (pw - cw) * mw, da = ca + (pa - ca) * ma;
;         dw.x = fast_tanh(dw.x); dw.y = fast_tanh(dw.y); dw.z = fast_tanh(dw.z); dw.w = fast_tanh(dw.w);
;         *(LAS v2u*)(TD + tok * 64 + c4) = pk4(dw); *(LAS v2u*)(DA + tok * 64 + c4) = pk4(da);
;     }
;     __syncthreads();
;     LAS unsigned char* lw_ = F.lds + 8192 + F.wave * 10240;
;     for (int q = 0; q < 4; ++q) { const int hh = q >> 1, rb = q & 1; rw_chunk_prep(a, 2 * F.wave + hh, t0 + rb * 16, TD + rb * 16 * 64, DA + rb * 16 * 64, lw_, F.lane); }
.LBB0_327:
	s_or_b64 exec, exec, s[2:3]
	global_load_dwordx4 v[16:19], v[70:71], off
	global_load_dwordx4 v[20:23], v[72:73], off
	s_waitcnt vmcnt(2)
	v_sub_f32_e32 v9, v9, v5
	v_sub_f32_e32 v8, v8, v4
	v_sub_f32_e32 v11, v11, v7
	v_sub_f32_e32 v10, v10, v6
	s_and_b32 s59, s99, 1
	s_lshl_b32 s58, s59, 4
	s_waitcnt vmcnt(1)
	v_pk_fma_f32 v[4:5], v[8:9], v[16:17], v[4:5]
	s_nop 0
	v_med3_f32 v4, v4, s41, v184
	v_med3_f32 v5, v5, s41, v184
	v_add_f32_e32 v4, v4, v4
	v_add_f32_e32 v5, v5, v5
	v_mul_f32_e32 v4, 0x3fb8aa3b, v4
	v_mul_f32_e32 v5, 0x3fb8aa3b, v5
	v_exp_f32_e32 v4, v4
	v_exp_f32_e32 v5, v5
	v_sub_f32_e32 v9, v13, v1
	v_sub_f32_e32 v8, v12, v0
	v_pk_fma_f32 v[6:7], v[10:11], v[18:19], v[6:7]
	v_sub_f32_e32 v11, v15, v3
	v_sub_f32_e32 v10, v14, v2
	s_waitcnt vmcnt(0)
	v_pk_fma_f32 v[0:1], v[8:9], v[20:21], v[0:1]
	v_pk_add_f32 v[8:9], v[4:5], -1.0 op_sel_hi:[1,0]
	v_pk_add_f32 v[4:5], v[4:5], 1.0 op_sel_hi:[1,0]
	v_pk_fma_f32 v[2:3], v[10:11], v[22:23], v[2:3]
	v_div_scale_f32 v10, s[2:3], v5, v5, v9
	v_rcp_f32_e32 v11, v10
	v_cvt_pk_bf16_f32 v0, v0, v1
	v_cvt_pk_bf16_f32 v1, v2, v3
	v_fma_f32 v12, -v10, v11, 1.0
	v_fmac_f32_e32 v11, v12, v11
	v_div_scale_f32 v12, vcc, v9, v5, v9
	v_mul_f32_e32 v13, v12, v11
	v_fma_f32 v14, -v10, v13, v12
	v_fmac_f32_e32 v13, v14, v11
	v_fma_f32 v10, -v10, v13, v12
	v_div_fmas_f32 v10, v10, v11, v13
	v_div_fixup_f32 v9, v10, v5, v9
	v_div_scale_f32 v5, s[2:3], v4, v4, v8
	v_rcp_f32_e32 v10, v5
	s_nop 0
	v_fma_f32 v11, -v5, v10, 1.0
	v_fmac_f32_e32 v10, v11, v10
	v_div_scale_f32 v11, vcc, v8, v4, v8
	v_mul_f32_e32 v12, v11, v10
	v_fma_f32 v13, -v5, v12, v11
	v_fmac_f32_e32 v12, v13, v10
	v_fma_f32 v5, -v5, v12, v11
	v_div_fmas_f32 v5, v5, v10, v12
	v_div_fixup_f32 v8, v5, v4, v8
	v_med3_f32 v4, v6, s41, v184
	v_med3_f32 v5, v7, s41, v184
	v_add_f32_e32 v4, v4, v4
	v_add_f32_e32 v5, v5, v5
	v_mul_f32_e32 v4, 0x3fb8aa3b, v4
	v_mul_f32_e32 v5, 0x3fb8aa3b, v5
	v_exp_f32_e32 v4, v4
	v_exp_f32_e32 v5, v5
	s_nop 0
	v_pk_add_f32 v[6:7], v[4:5], -1.0 op_sel_hi:[1,0]
	v_pk_add_f32 v[4:5], v[4:5], 1.0 op_sel_hi:[1,0]
	s_nop 0
	v_div_scale_f32 v10, s[2:3], v5, v5, v7
	v_rcp_f32_e32 v11, v10
	s_nop 0
	v_fma_f32 v12, -v10, v11, 1.0
	v_fmac_f32_e32 v11, v12, v11
	v_div_scale_f32 v12, vcc, v7, v5, v7
	v_mul_f32_e32 v13, v12, v11
	v_fma_f32 v14, -v10, v13, v12
	v_fmac_f32_e32 v13, v14, v11
	v_fma_f32 v10, -v10, v13, v12
	v_div_fmas_f32 v10, v10, v11, v13
	v_div_fixup_f32 v5, v10, v5, v7
	v_div_scale_f32 v7, s[2:3], v4, v4, v6
	v_rcp_f32_e32 v10, v7
	s_nop 0
	v_fma_f32 v11, -v7, v10, 1.0
	v_fmac_f32_e32 v10, v11, v10
	v_div_scale_f32 v11, vcc, v6, v4, v6
	v_mul_f32_e32 v12, v11, v10
	v_fma_f32 v13, -v7, v12, v11
	v_fmac_f32_e32 v12, v13, v10
	v_fma_f32 v7, -v7, v12, v11
	v_div_fmas_f32 v7, v7, v10, v12
	v_div_fixup_f32 v6, v7, v4, v6
	v_cvt_pk_bf16_f32 v4, v8, v9
	v_cvt_pk_bf16_f32 v5, v6, v5
	ds_write2st64_b64 v65, v[4:5], v[0:1] offset1:8
	s_waitcnt lgkmcnt(0)
	s_barrier
	s_branch .LBB0_329
.LBB0_328:
	s_or_b64 exec, exec, s[26:27]
	s_waitcnt lgkmcnt(0)
	s_cmp_eq_u32 s98, 1
	s_cselect_b32 s100, 2, 1
	s_add_i32 s59, s59, s100
	s_lshl_b32 s100, s100, 4
	s_add_i32 s58, s58, s100
	s_cmp_lt_u32 s59, 4
	s_cbranch_scc0 .LBB0_322

; #define SP_BAR() asm volatile("s_waitcnt lgkmcnt(0)\n\ts_barrier" ::: "memory")
; #define SP_WAIT() asm volatile("s_waitcnt vmcnt(36)" ::: "memory")
; __device__ __forceinline__ void p3_rwkv_state(Frame& F, const Args& a) {
;     ...
;     if (loader) {
;         DmaPtrs P; rw_dma_init(a, P, head, ib, lw, lane);
;         for (int n = 0; n < SP_D; ++n) rw_dma_issue(P, lw, lane, lds0 + (unsigned)(n % SP_R) * SP_SLOT);
;         SP_WAIT();
;         SP_BAR();
;         for (int n = 0; n < NC; n += 2) {
;             if (n + SP_D + 1 < NC) { rw_dma_issue(P, lw, lane, lds0 + (unsigned)((n + SP_D) % SP_R) * SP_SLOT); rw_dma_issue(P, lw, lane, lds0 + (unsigned)((n + SP_D + 1) % SP_R) * SP_SLOT); SP_WAIT(); }
.Lscan_ldbig_pro:
	s_add_i32 s16, s15, s14
	s_mov_b32 m0, s16
	s_add_i32 s15, s15, 0x2800
	global_load_lds_dwordx4 v[2:3], off
	global_load_lds_dwordx4 v[2:3], off offset:1024
	s_cmp_eq_u32 s15, 0x25800
	s_cselect_b32 s15, 0, s15
	v_lshl_add_u64 v[2:3], v[2:3], 0, s[6:7]
	s_add_i32 s18, s18, 1
	s_cmp_lt_u32 s18, 12
	s_cbranch_scc1 .Lscan_ldbig_pro
	s_waitcnt vmcnt(18)
	s_barrier
	s_mov_b32 s18, 0
	s_movk_i32 s17, 0x200

; #define SP_WAIT() asm volatile("s_waitcnt vmcnt(36)" ::: "memory")
; __device__ __forceinline__ void p3_rwkv_state(Frame& F, const Args& a) {
;     ...
;         for (int n = 0; n < NC; n += 2) {
;             if (n + SP_D + 1 < NC) { rw_dma_issue(P, lw, lane, lds0 + (unsigned)((n + SP_D) % SP_R) * SP_SLOT); rw_dma_issue(P, lw, lane, lds0 + (unsigned)((n + SP_D + 1) % SP_R) * SP_SLOT); SP_WAIT(); }
;             else asm volatile("s_waitcnt vmcnt(0)" ::: "memory");
.Lscan_ldbig_chk:
	s_add_i32 s24, s18, 13
	s_cmp_lt_u32 s24, s17
	s_cbranch_scc1 .Lscan_ldbig_go
	v_add_u32_e32 v12, s17, v76
	v_lshlrev_b32_e32 v13, 2, v12
	v_add_u32_e32 v13, 0x8000, v13
	global_load_dword v13, v13, s[90:91] sc1
	s_movk_i32 s24, 0x3ff
	s_waitcnt vmcnt(0)
	v_cmp_ne_u32_e64 s[20:21], 0, v13
	v_cmp_lt_u32_e64 s[22:23], s24, v12
	s_nop 1
	s_or_b64 s[20:21], s[20:21], s[22:23]
	s_not_b64 s[20:21], s[20:21]
	s_ff1_i32_b64 s24, s[20:21]
	s_cmp_eq_u32 s24, -1
	s_cselect_b32 s24, 64, s24
	s_add_i32 s17, s17, s24
	buffer_inv sc1
	s_waitcnt vmcnt(0)
	s_cmp_lg_u32 s24, 0
	s_cbranch_scc1 .Lscan_ldbig_chk
	s_sleep 8
	s_branch .Lscan_ldbig_chk

; #define SP_BAR() asm volatile("s_waitcnt lgkmcnt(0)\n\ts_barrier" ::: "memory")
; #define SP_WAIT() asm volatile("s_waitcnt vmcnt(36)" ::: "memory")
; __device__ __forceinline__ void p3_rwkv_state(Frame& F, const Args& a) {
;     ...
;     if (loader) {
;         DmaPtrs P; rw_dma_init(a, P, head, ib, lw, lane);
;         for (int n = 0; n < SP_D; ++n) rw_dma_issue(P, lw, lane, lds0 + (unsigned)(n % SP_R) * SP_SLOT);
;         SP_WAIT();
;         SP_BAR();
.Lscan_ldsmall_pro:
	s_add_i32 s16, s15, 0x2000
	s_mov_b32 m0, s16
	s_mov_b32 exec_hi, 0
	s_add_i32 s15, s15, 0x2800
	global_load_lds_dwordx4 v[2:3], off
	global_load_lds_dwordx4 v[4:5], off offset:512
	global_load_lds_dwordx4 v[6:7], off offset:1024
	s_mov_b32 exec_lo, 0xffff
	s_cmp_eq_u32 s15, 0x25800
	global_load_lds_dwordx4 v[8:9], off offset:1536
	s_mov_b64 exec, -1
	s_cselect_b32 s15, 0, s15
	v_lshl_add_u64 v[2:3], v[2:3], 0, s[6:7]
	v_lshl_add_u64 v[4:5], v[4:5], 0, s[6:7]
	v_lshl_add_u64 v[6:7], v[6:7], 0, s[6:7]
	v_lshl_add_u64 v[8:9], v[8:9], 0, s[10:11]
	s_add_i32 s18, s18, 1
	s_cmp_lt_u32 s18, 12
	s_cbranch_scc1 .Lscan_ldsmall_pro
	s_waitcnt vmcnt(36)
	s_barrier
	s_mov_b32 s18, 0
	s_movk_i32 s17, 0x200
